# speedup vs baseline: 1.0238x; 1.0019x over previous
; #define G_STAGE(bufoff, gbase) do { _Pragma("unroll") for (int _i = 0; _i < 2; ++_i) \
;     __builtin_amdgcn_global_load_lds((const unsigned*)((const char*)(gbase) + voffA[_i]), (LAS unsigned*)(lds + (bufoff) + ldsw + _i * 8192), 16, 0, 0); } while (0)
; #define G_LDA(dst, b, h) do { _Pragma("unroll") for (int m = 0; m < 4; ++m) _Pragma("unroll") for (int k = 0; k < 2; ++k) dst[m][k] = *(const LAS bf16x8*)(lds + G_SA(b, h) + aoff + m * 2048 + k * 1024); } while (0)
; #define G_LDB(dst, b, h) do { _Pragma("unroll") for (int n = 0; n < 2; ++n) _Pragma("unroll") for (int k = 0; k < 2; ++k) dst[n][k] = *(const LAS bf16x8*)(lds + G_SB(b, h) + boff + n * 2048 + k * 1024); } while (0)
; #define G_MMA(ai, bj, At, Bt) do { __builtin_amdgcn_s_setprio(1); _Pragma("unroll") for (int m = 0; m < 4; ++m) _Pragma("unroll") for (int n = 0; n < 2; ++n) _Pragma("unroll") for (int k = 0; k < 2; ++k) \
;     acc[ai][bj][m][n] = __builtin_amdgcn_mfma_f32_16x16x32_bf16(Bt[n][k], At[m][k], acc[ai][bj][m][n], 0, 0, 0); __builtin_amdgcn_s_setprio(0); } while (0)
; #define G_WAIT_V(n) asm volatile("s_waitcnt vmcnt(" #n ")" ::: "memory")
; #define G_WAIT_L(n) asm volatile("s_waitcnt lgkmcnt(" #n ")" ::: "memory")
; #define G_BAR __builtin_amdgcn_s_barrier()
; #define G_SCHED __builtin_amdgcn_sched_barrier(0)
; template <int MODE>
; __device__ __forceinline__ void gemm_phase(const Params& p, int layer, char* lds_generic) {
;     ...
;       G_LDB(B0, 0, 0); G_SCHED; G_LDA(At, 0, 0); G_STAGE(G_SA(1, 1), a1 + hstep);
;       G_WAIT_L(8); G_BAR; G_WAIT_L(0); G_MMA(0, 0, At, B0); G_BAR; G_SCHED;
;       G_LDB(B1, 0, 1); G_STAGE(G_SB(0, 0), b2);
;       G_BAR; G_WAIT_L(0); G_MMA(0, 1, At, B1); G_BAR;
;       G_LDA(At, 0, 1); G_STAGE(G_SA(0, 0), a2);
;       G_BAR; G_WAIT_L(0); G_MMA(1, 0, At, B0); G_BAR; G_SCHED;
;       G_STAGE(G_SB(0, 1), b2 + hstep);
;       G_WAIT_V(6); G_BAR; G_MMA(1, 1, At, B1); G_BAR;
;       G_LDB(B0, 1, 0); G_SCHED; G_LDA(At, 1, 0); G_STAGE(G_SA(0, 1), a2 + hstep);
;       G_WAIT_L(8); G_BAR; G_WAIT_L(0); G_MMA(0, 0, At, B0); G_BAR; G_SCHED;
.LBB0_103:
	v_or_b32_e32 v134, 0x10000, v140
	v_add_u32_e32 v142, 0x10400, v140
	v_add_u32_e32 v146, 0x10800, v140
	v_add_u32_e32 v150, 0x10c00, v140
	ds_read_b128 v[134:137], v134
	ds_read_b128 v[142:145], v142
	ds_read_b128 v[146:149], v146
	ds_read_b128 v[150:153], v150
	s_add_u32 s12, vcc_lo, 0xfff80080
	s_addc_u32 s13, vcc_hi, -1
	s_cmp_eq_u32 s9, 28
	s_cselect_b32 s79, s2, s13
	s_cselect_b32 s78, s69, s12
	s_cselect_b32 s77, s71, s60
	s_cselect_b32 s76, s88, s89
	v_lshl_add_u64 v[186:187], vcc, 0, v[130:131]
	s_add_i32 m0, s8, 0xc000
	ds_read_b128 v[154:157], v139
	ds_read_b128 v[158:161], v139 offset:1024
	ds_read_b128 v[162:165], v139 offset:2048
	ds_read_b128 v[166:169], v139 offset:3072
	ds_read_b128 v[170:173], v139 offset:4096
	ds_read_b128 v[174:177], v139 offset:5120
	ds_read_b128 v[178:181], v139 offset:6144
	ds_read_b128 v[182:185], v139 offset:7168
	global_load_lds_dwordx4 v[186:187], off
	v_lshl_add_u64 v[186:187], vcc, 0, v[132:133]
	s_add_i32 m0, s8, 0xe000
	s_nop 0
	global_load_lds_dwordx4 v[186:187], off
	s_waitcnt lgkmcnt(8)
	s_barrier
	s_waitcnt lgkmcnt(0)
	s_setprio 1
	s_waitcnt lgkmcnt(0)
	v_mfma_f32_16x16x32_bf16 v[124:127], v[134:137], v[154:157], v[124:127]
	v_mfma_f32_16x16x32_bf16 v[120:123], v[146:149], v[154:157], v[120:123]
	v_mfma_f32_16x16x32_bf16 v[108:111], v[134:137], v[162:165], v[108:111]
	v_mfma_f32_16x16x32_bf16 v[104:107], v[146:149], v[162:165], v[104:107]
	v_mfma_f32_16x16x32_bf16 v[92:95], v[134:137], v[170:173], v[92:95]
	v_mfma_f32_16x16x32_bf16 v[88:91], v[146:149], v[170:173], v[88:91]
	v_mfma_f32_16x16x32_bf16 v[76:79], v[134:137], v[178:181], v[76:79]
	v_mfma_f32_16x16x32_bf16 v[72:75], v[146:149], v[178:181], v[72:75]
	v_mfma_f32_16x16x32_bf16 v[124:127], v[142:145], v[158:161], v[124:127]
	v_mfma_f32_16x16x32_bf16 v[120:123], v[150:153], v[158:161], v[120:123]
	v_mfma_f32_16x16x32_bf16 v[108:111], v[142:145], v[166:169], v[108:111]
	v_mfma_f32_16x16x32_bf16 v[104:107], v[150:153], v[166:169], v[104:107]
	v_mfma_f32_16x16x32_bf16 v[92:95], v[142:145], v[174:177], v[92:95]
	v_mfma_f32_16x16x32_bf16 v[88:91], v[150:153], v[174:177], v[88:91]
	v_mfma_f32_16x16x32_bf16 v[76:79], v[142:145], v[182:185], v[76:79]
	v_mfma_f32_16x16x32_bf16 v[72:75], v[150:153], v[182:185], v[72:75]
	s_setprio 0
	s_barrier
	v_or_b32_e32 v186, 0x14000, v140
	v_add_u32_e32 v190, 0x14400, v140
	ds_read_b128 v[186:189], v186
	ds_read_b128 v[194:197], v190
	v_add_u32_e32 v190, 0x14800, v140
	v_add_u32_e32 v191, 0x14c00, v140
	s_mov_b32 m0, s92
	ds_read_b128 v[198:201], v190
	ds_read_b128 v[202:205], v191
	v_lshl_add_u64 v[190:191], s[76:77], 0, v[192:193]
	global_load_lds_dwordx4 v[190:191], off
	v_lshl_add_u64 v[206:207], s[76:77], 0, v[128:129]
	s_mov_b32 m0, s94
	s_nop 0
	global_load_lds_dwordx4 v[206:207], off
	s_barrier
	s_waitcnt lgkmcnt(0)
	s_setprio 1
	s_waitcnt lgkmcnt(0)
	v_mfma_f32_16x16x32_bf16 v[116:119], v[186:189], v[154:157], v[116:119]
	v_mfma_f32_16x16x32_bf16 v[112:115], v[198:201], v[154:157], v[112:115]
	v_mfma_f32_16x16x32_bf16 v[100:103], v[186:189], v[162:165], v[100:103]
	v_mfma_f32_16x16x32_bf16 v[96:99], v[198:201], v[162:165], v[96:99]
	v_mfma_f32_16x16x32_bf16 v[84:87], v[186:189], v[170:173], v[84:87]
	v_mfma_f32_16x16x32_bf16 v[80:83], v[198:201], v[170:173], v[80:83]
	v_mfma_f32_16x16x32_bf16 v[68:71], v[186:189], v[178:181], v[68:71]
	v_mfma_f32_16x16x32_bf16 v[64:67], v[198:201], v[178:181], v[64:67]
	v_mfma_f32_16x16x32_bf16 v[116:119], v[194:197], v[158:161], v[116:119]
	v_mfma_f32_16x16x32_bf16 v[112:115], v[202:205], v[158:161], v[112:115]
	v_mfma_f32_16x16x32_bf16 v[100:103], v[194:197], v[166:169], v[100:103]
	v_mfma_f32_16x16x32_bf16 v[96:99], v[202:205], v[166:169], v[96:99]
	v_mfma_f32_16x16x32_bf16 v[84:87], v[194:197], v[174:177], v[84:87]
	v_mfma_f32_16x16x32_bf16 v[80:83], v[202:205], v[174:177], v[80:83]
	v_mfma_f32_16x16x32_bf16 v[68:71], v[194:197], v[182:185], v[68:71]
	v_mfma_f32_16x16x32_bf16 v[64:67], v[202:205], v[182:185], v[64:67]
	s_setprio 0
	s_mov_b32 m0, s8
	v_lshl_add_u64 v[208:209], s[78:79], 0, v[192:193]
	s_barrier
	ds_read_b128 v[154:157], v139 offset:16384
	ds_read_b128 v[158:161], v139 offset:17408
	ds_read_b128 v[162:165], v139 offset:18432
	ds_read_b128 v[166:169], v139 offset:19456
	ds_read_b128 v[170:173], v139 offset:20480
	ds_read_b128 v[174:177], v139 offset:21504
	ds_read_b128 v[178:181], v139 offset:22528
	ds_read_b128 v[182:185], v139 offset:23552
	global_load_lds_dwordx4 v[208:209], off
	v_lshl_add_u64 v[210:211], s[78:79], 0, v[128:129]
	s_mov_b32 m0, s33
	s_nop 0
	global_load_lds_dwordx4 v[210:211], off
	s_barrier
	s_waitcnt lgkmcnt(0)
	s_setprio 1
	s_waitcnt lgkmcnt(0)
	v_mfma_f32_16x16x32_bf16 v[60:63], v[134:137], v[154:157], v[60:63]
	v_mfma_f32_16x16x32_bf16 v[56:59], v[146:149], v[154:157], v[56:59]
	v_mfma_f32_16x16x32_bf16 v[44:47], v[134:137], v[162:165], v[44:47]
	v_mfma_f32_16x16x32_bf16 v[40:43], v[146:149], v[162:165], v[40:43]
	v_mfma_f32_16x16x32_bf16 v[28:31], v[134:137], v[170:173], v[28:31]
	v_mfma_f32_16x16x32_bf16 v[24:27], v[146:149], v[170:173], v[24:27]
	v_mfma_f32_16x16x32_bf16 v[12:15], v[134:137], v[178:181], v[12:15]
	v_mfma_f32_16x16x32_bf16 v[8:11], v[146:149], v[178:181], v[8:11]
	v_mfma_f32_16x16x32_bf16 v[60:63], v[142:145], v[158:161], v[60:63]
	v_mfma_f32_16x16x32_bf16 v[56:59], v[150:153], v[158:161], v[56:59]
	v_mfma_f32_16x16x32_bf16 v[44:47], v[142:145], v[166:169], v[44:47]
	v_mfma_f32_16x16x32_bf16 v[40:43], v[150:153], v[166:169], v[40:43]
	v_mfma_f32_16x16x32_bf16 v[28:31], v[142:145], v[174:177], v[28:31]
	v_mfma_f32_16x16x32_bf16 v[24:27], v[150:153], v[174:177], v[24:27]
	v_mfma_f32_16x16x32_bf16 v[12:15], v[142:145], v[182:185], v[12:15]
	v_mfma_f32_16x16x32_bf16 v[8:11], v[150:153], v[182:185], v[8:11]
	s_setprio 0
	s_barrier
; #define G_STAGE(bufoff, gbase) do { _Pragma("unroll") for (int _i = 0; _i < 2; ++_i) \
;     __builtin_amdgcn_global_load_lds((const unsigned*)((const char*)(gbase) + voffA[_i]), (LAS unsigned*)(lds + (bufoff) + ldsw + _i * 8192), 16, 0, 0); } while (0)
; #define G_LDA(dst, b, h) do { _Pragma("unroll") for (int m = 0; m < 4; ++m) _Pragma("unroll") for (int k = 0; k < 2; ++k) dst[m][k] = *(const LAS bf16x8*)(lds + G_SA(b, h) + aoff + m * 2048 + k * 1024); } while (0)
; #define G_LDB(dst, b, h) do { _Pragma("unroll") for (int n = 0; n < 2; ++n) _Pragma("unroll") for (int k = 0; k < 2; ++k) dst[n][k] = *(const LAS bf16x8*)(lds + G_SB(b, h) + boff + n * 2048 + k * 1024); } while (0)
; #define G_MMA(ai, bj, At, Bt) do { __builtin_amdgcn_s_setprio(1); _Pragma("unroll") for (int m = 0; m < 4; ++m) _Pragma("unroll") for (int n = 0; n < 2; ++n) _Pragma("unroll") for (int k = 0; k < 2; ++k) \
;     acc[ai][bj][m][n] = __builtin_amdgcn_mfma_f32_16x16x32_bf16(Bt[n][k], At[m][k], acc[ai][bj][m][n], 0, 0, 0); __builtin_amdgcn_s_setprio(0); } while (0)
; #define G_WAIT_V(n) asm volatile("s_waitcnt vmcnt(" #n ")" ::: "memory")
; #define G_WAIT_L(n) asm volatile("s_waitcnt lgkmcnt(" #n ")" ::: "memory")
; #define G_BAR __builtin_amdgcn_s_barrier()
; #define G_SCHED __builtin_amdgcn_sched_barrier(0)
; template <int MODE>
; __device__ __forceinline__ void gemm_phase(const Params& p, int layer, char* lds_generic) {
;     ...
;       G_WAIT_V(6); G_BAR; G_MMA(1, 1, At, B1); G_BAR;
;       G_LDB(B0, 1, 0); G_SCHED; G_LDA(At, 1, 0); G_STAGE(G_SA(0, 1), a2 + hstep);
;       G_WAIT_L(8); G_BAR; G_WAIT_L(0); G_MMA(0, 0, At, B0); G_BAR; G_SCHED;
;       G_LDB(B1, 1, 1); G_STAGE(G_SB(1, 0), b3);
;       G_BAR; G_WAIT_L(0); G_MMA(0, 1, At, B1); G_BAR;
;       G_LDA(At, 1, 1); G_STAGE(G_SA(1, 0), a3);
;       G_BAR; G_WAIT_L(0); G_MMA(1, 0, At, B0); G_BAR; G_SCHED;
;       G_STAGE(G_SB(1, 1), b3 + hstep);
	s_add_u32 s66, s76, 0x80000
	s_addc_u32 s67, s77, 0
	s_mov_b32 m0, s1
	v_lshl_add_u64 v[134:135], s[66:67], 0, v[192:193]
	global_load_lds_dwordx4 v[134:135], off
	v_lshl_add_u64 v[134:135], s[66:67], 0, v[128:129]
	s_mov_b32 m0, s34
	s_nop 0
	global_load_lds_dwordx4 v[134:135], off
	s_waitcnt vmcnt(6)
	s_barrier
	s_setprio 1
	v_mfma_f32_16x16x32_bf16 v[52:55], v[186:189], v[154:157], v[52:55]
	v_mfma_f32_16x16x32_bf16 v[48:51], v[198:201], v[154:157], v[48:51]
	v_mfma_f32_16x16x32_bf16 v[36:39], v[186:189], v[162:165], v[36:39]
	v_mfma_f32_16x16x32_bf16 v[32:35], v[198:201], v[162:165], v[32:35]
	v_mfma_f32_16x16x32_bf16 v[20:23], v[186:189], v[170:173], v[20:23]
	v_mfma_f32_16x16x32_bf16 v[16:19], v[198:201], v[170:173], v[16:19]
	v_mfma_f32_16x16x32_bf16 v[4:7], v[186:189], v[178:181], v[4:7]
	v_mfma_f32_16x16x32_bf16 v[0:3], v[198:201], v[178:181], v[0:3]
	v_mfma_f32_16x16x32_bf16 v[52:55], v[194:197], v[158:161], v[52:55]
	v_mfma_f32_16x16x32_bf16 v[48:51], v[202:205], v[158:161], v[48:51]
	v_mfma_f32_16x16x32_bf16 v[36:39], v[194:197], v[166:169], v[36:39]
	v_mfma_f32_16x16x32_bf16 v[32:35], v[202:205], v[166:169], v[32:35]
	v_mfma_f32_16x16x32_bf16 v[20:23], v[194:197], v[174:177], v[20:23]
	v_mfma_f32_16x16x32_bf16 v[16:19], v[202:205], v[174:177], v[16:19]
	v_mfma_f32_16x16x32_bf16 v[4:7], v[194:197], v[182:185], v[4:7]
	v_mfma_f32_16x16x32_bf16 v[0:3], v[202:205], v[182:185], v[0:3]
	s_setprio 0
	v_or_b32_e32 v134, 0x18000, v140
	v_add_u32_e32 v142, 0x18400, v140
	v_add_u32_e32 v146, 0x18800, v140
	v_add_u32_e32 v150, 0x18c00, v140
	s_barrier
	ds_read_b128 v[134:137], v134
	ds_read_b128 v[142:145], v142
	ds_read_b128 v[146:149], v146
	ds_read_b128 v[150:153], v150
	s_add_u32 s66, s78, 0x80000
	s_addc_u32 s67, s79, 0
	s_mov_b32 m0, s35
	v_lshl_add_u64 v[186:187], s[66:67], 0, v[192:193]
	ds_read_b128 v[154:157], v139 offset:32768
	ds_read_b128 v[158:161], v139 offset:33792
	ds_read_b128 v[162:165], v139 offset:34816
	ds_read_b128 v[166:169], v139 offset:35840
	ds_read_b128 v[170:173], v139 offset:36864
	ds_read_b128 v[174:177], v139 offset:37888
	ds_read_b128 v[178:181], v139 offset:38912
	ds_read_b128 v[182:185], v139 offset:39936
	global_load_lds_dwordx4 v[186:187], off
	v_lshl_add_u64 v[186:187], s[66:67], 0, v[128:129]
	s_mov_b32 m0, s4
	s_nop 0
	global_load_lds_dwordx4 v[186:187], off
	s_waitcnt lgkmcnt(8)
	s_barrier
	s_waitcnt lgkmcnt(0)
	s_setprio 1
	s_waitcnt lgkmcnt(0)
	v_mfma_f32_16x16x32_bf16 v[124:127], v[134:137], v[154:157], v[124:127]
	v_mfma_f32_16x16x32_bf16 v[120:123], v[146:149], v[154:157], v[120:123]
	v_mfma_f32_16x16x32_bf16 v[108:111], v[134:137], v[162:165], v[108:111]
	v_mfma_f32_16x16x32_bf16 v[104:107], v[146:149], v[162:165], v[104:107]
	v_mfma_f32_16x16x32_bf16 v[92:95], v[134:137], v[170:173], v[92:95]
	v_mfma_f32_16x16x32_bf16 v[88:91], v[146:149], v[170:173], v[88:91]
	v_mfma_f32_16x16x32_bf16 v[76:79], v[134:137], v[178:181], v[76:79]
	v_mfma_f32_16x16x32_bf16 v[72:75], v[146:149], v[178:181], v[72:75]
	v_mfma_f32_16x16x32_bf16 v[124:127], v[142:145], v[158:161], v[124:127]
	v_mfma_f32_16x16x32_bf16 v[120:123], v[150:153], v[158:161], v[120:123]
	v_mfma_f32_16x16x32_bf16 v[108:111], v[142:145], v[166:169], v[108:111]
	v_mfma_f32_16x16x32_bf16 v[104:107], v[150:153], v[166:169], v[104:107]
	v_mfma_f32_16x16x32_bf16 v[92:95], v[142:145], v[174:177], v[92:95]
	v_mfma_f32_16x16x32_bf16 v[88:91], v[150:153], v[174:177], v[88:91]
	v_mfma_f32_16x16x32_bf16 v[76:79], v[142:145], v[182:185], v[76:79]
	v_mfma_f32_16x16x32_bf16 v[72:75], v[150:153], v[182:185], v[72:75]
	s_setprio 0
	s_barrier
	s_mov_b32 m0, s5
	v_or_b32_e32 v186, 0x1c000, v140
	v_add_u32_e32 v194, 0x1c400, v140
	v_add_u32_e32 v198, 0x1c800, v140
	v_add_u32_e32 v202, 0x1cc00, v140
	v_lshl_add_u64 v[190:191], v[190:191], 0, s[90:91]
	ds_read_b128 v[186:189], v186
	ds_read_b128 v[194:197], v194
	ds_read_b128 v[198:201], v198
	ds_read_b128 v[202:205], v202
	global_load_lds_dwordx4 v[190:191], off
	v_lshl_add_u64 v[190:191], v[206:207], 0, s[90:91]
	s_mov_b32 m0, s82
	s_nop 0
	global_load_lds_dwordx4 v[190:191], off
	s_barrier
	s_waitcnt lgkmcnt(0)
	s_setprio 1
	s_waitcnt lgkmcnt(0)
	v_mfma_f32_16x16x32_bf16 v[116:119], v[186:189], v[154:157], v[116:119]
	v_mfma_f32_16x16x32_bf16 v[112:115], v[198:201], v[154:157], v[112:115]
	v_mfma_f32_16x16x32_bf16 v[100:103], v[186:189], v[162:165], v[100:103]
	v_mfma_f32_16x16x32_bf16 v[96:99], v[198:201], v[162:165], v[96:99]
	v_mfma_f32_16x16x32_bf16 v[84:87], v[186:189], v[170:173], v[84:87]
	v_mfma_f32_16x16x32_bf16 v[80:83], v[198:201], v[170:173], v[80:83]
	v_mfma_f32_16x16x32_bf16 v[68:71], v[186:189], v[178:181], v[68:71]
	v_mfma_f32_16x16x32_bf16 v[64:67], v[198:201], v[178:181], v[64:67]
	v_mfma_f32_16x16x32_bf16 v[116:119], v[194:197], v[158:161], v[116:119]
	v_mfma_f32_16x16x32_bf16 v[112:115], v[202:205], v[158:161], v[112:115]
	v_mfma_f32_16x16x32_bf16 v[100:103], v[194:197], v[166:169], v[100:103]
	v_mfma_f32_16x16x32_bf16 v[96:99], v[202:205], v[166:169], v[96:99]
	v_mfma_f32_16x16x32_bf16 v[84:87], v[194:197], v[174:177], v[84:87]
	v_mfma_f32_16x16x32_bf16 v[80:83], v[202:205], v[174:177], v[80:83]
	v_mfma_f32_16x16x32_bf16 v[68:71], v[194:197], v[182:185], v[68:71]
	v_mfma_f32_16x16x32_bf16 v[64:67], v[202:205], v[182:185], v[64:67]
	s_setprio 0
	s_mov_b32 m0, s83
	v_lshl_add_u64 v[190:191], v[208:209], 0, s[90:91]
	s_barrier
	ds_read_b128 v[154:157], v139 offset:49152
	ds_read_b128 v[158:161], v139 offset:50176
	ds_read_b128 v[162:165], v139 offset:51200
	ds_read_b128 v[166:169], v139 offset:52224
	ds_read_b128 v[170:173], v139 offset:53248
	ds_read_b128 v[174:177], v139 offset:54272
	ds_read_b128 v[178:181], v139 offset:55296
	ds_read_b128 v[182:185], v139 offset:56320
	global_load_lds_dwordx4 v[190:191], off
	v_lshl_add_u64 v[190:191], v[210:211], 0, s[90:91]
	s_mov_b32 m0, s84
	s_nop 0
	global_load_lds_dwordx4 v[190:191], off
	s_barrier
;   __device__ __forceinline__ bf16_t* XB() const { return (bf16_t*)(ws + 328 * MB); }
; __device__ __forceinline__ float bflo(unsigned w) { return __uint_as_float(w << 16); }
; __device__ __forceinline__ float bfhi(unsigned w) { return __uint_as_float(w & 0xffff0000u); }
; #define G_STAGE(bufoff, gbase) do { _Pragma("unroll") for (int _i = 0; _i < 2; ++_i) \
;     __builtin_amdgcn_global_load_lds((const unsigned*)((const char*)(gbase) + voffA[_i]), (LAS unsigned*)(lds + (bufoff) + ldsw + _i * 8192), 16, 0, 0); } while (0)
; #define G_LDA(dst, b, h) do { _Pragma("unroll") for (int m = 0; m < 4; ++m) _Pragma("unroll") for (int k = 0; k < 2; ++k) dst[m][k] = *(const LAS bf16x8*)(lds + G_SA(b, h) + aoff + m * 2048 + k * 1024); } while (0)
; #define G_MMA(ai, bj, At, Bt) do { __builtin_amdgcn_s_setprio(1); _Pragma("unroll") for (int m = 0; m < 4; ++m) _Pragma("unroll") for (int n = 0; n < 2; ++n) _Pragma("unroll") for (int k = 0; k < 2; ++k) \
;     acc[ai][bj][m][n] = __builtin_amdgcn_mfma_f32_16x16x32_bf16(Bt[n][k], At[m][k], acc[ai][bj][m][n], 0, 0, 0); __builtin_amdgcn_s_setprio(0); } while (0)
; #define G_WAIT_V(n) asm volatile("s_waitcnt vmcnt(" #n ")" ::: "memory")
; #define G_BAR __builtin_amdgcn_s_barrier()
; template <int MODE>
; __device__ __forceinline__ void gemm_epilogue(const Params& p, int layer, const f32x4 (&acc)[2][2][4][2], int pm, int pn, int wr, int wc, int fr, int fq) {
;     ...
;         for (int bj = 0; bj < 2; ++bj) { const int col = pn * 256 + bj * 128 + wc * 32 + 8 * fq;
;           bf16_t* xq = p.XB() + (size_t)row * DM + col; const u32x4 r = *(const u32x4*)xq; const f32x4 a0 = acc[ai][bj][m][0], a1 = acc[ai][bj][m][1];
;           const u32x4 w = {cvtpk(a0[0] + bflo(r[0]), a0[1] + bfhi(r[0])), cvtpk(a0[2] + bflo(r[1]), a0[3] + bfhi(r[1])), cvtpk(a1[0] + bflo(r[2]), a1[1] + bfhi(r[2])), cvtpk(a1[2] + bflo(r[3]), a1[3] + bfhi(r[3]))};
;           *(u32x4*)xq = w; }
; template <int MODE>
; __device__ __forceinline__ void gemm_phase(const Params& p, int layer, char* lds_generic) {
;     ...
;       G_BAR; G_WAIT_L(0); G_MMA(0, 1, At, B1); G_BAR;
;       G_LDA(At, 1, 1); G_STAGE(G_SA(1, 0), a3);
;       G_BAR; G_WAIT_L(0); G_MMA(1, 0, At, B0); G_BAR; G_SCHED;
;       G_STAGE(G_SB(1, 1), b3 + hstep);
;       G_WAIT_V(6); G_BAR; G_MMA(1, 1, At, B1); G_BAR;
;     }
;     gemm_epilogue<MODE>(p, layer, acc, cpm, cpn, wr, wc, fr, fq);
	s_waitcnt lgkmcnt(0)
	s_setprio 1
	s_waitcnt lgkmcnt(0)
	v_mfma_f32_16x16x32_bf16 v[60:63], v[134:137], v[154:157], v[60:63]
	v_mfma_f32_16x16x32_bf16 v[56:59], v[146:149], v[154:157], v[56:59]
	v_mfma_f32_16x16x32_bf16 v[44:47], v[134:137], v[162:165], v[44:47]
	v_mfma_f32_16x16x32_bf16 v[40:43], v[146:149], v[162:165], v[40:43]
	v_mfma_f32_16x16x32_bf16 v[28:31], v[134:137], v[170:173], v[28:31]
	v_mfma_f32_16x16x32_bf16 v[24:27], v[146:149], v[170:173], v[24:27]
	v_mfma_f32_16x16x32_bf16 v[12:15], v[134:137], v[178:181], v[12:15]
	v_mfma_f32_16x16x32_bf16 v[8:11], v[146:149], v[178:181], v[8:11]
	v_mfma_f32_16x16x32_bf16 v[60:63], v[142:145], v[158:161], v[60:63]
	v_mfma_f32_16x16x32_bf16 v[56:59], v[150:153], v[158:161], v[56:59]
	v_mfma_f32_16x16x32_bf16 v[44:47], v[142:145], v[166:169], v[44:47]
	v_mfma_f32_16x16x32_bf16 v[40:43], v[150:153], v[166:169], v[40:43]
	v_mfma_f32_16x16x32_bf16 v[28:31], v[142:145], v[174:177], v[28:31]
	v_mfma_f32_16x16x32_bf16 v[24:27], v[150:153], v[174:177], v[24:27]
	v_mfma_f32_16x16x32_bf16 v[12:15], v[142:145], v[182:185], v[12:15]
	v_mfma_f32_16x16x32_bf16 v[8:11], v[150:153], v[182:185], v[8:11]
	s_setprio 0
	s_barrier
	s_add_u32 s66, s76, 0x80080
	s_addc_u32 s67, s77, 0
	s_mov_b32 m0, s85
	v_lshl_add_u64 v[134:135], s[66:67], 0, v[192:193]
	global_load_lds_dwordx4 v[134:135], off
	v_lshl_add_u64 v[134:135], s[66:67], 0, v[128:129]
	s_mov_b32 m0, s80
	s_nop 0
	global_load_lds_dwordx4 v[134:135], off
	s_waitcnt vmcnt(6)
	s_barrier
	s_setprio 1
	v_mfma_f32_16x16x32_bf16 v[52:55], v[186:189], v[154:157], v[52:55]
	v_mfma_f32_16x16x32_bf16 v[48:51], v[198:201], v[154:157], v[48:51]
	v_mfma_f32_16x16x32_bf16 v[36:39], v[186:189], v[162:165], v[36:39]
	v_mfma_f32_16x16x32_bf16 v[32:35], v[198:201], v[162:165], v[32:35]
	v_mfma_f32_16x16x32_bf16 v[20:23], v[186:189], v[170:173], v[20:23]
	v_mfma_f32_16x16x32_bf16 v[16:19], v[198:201], v[170:173], v[16:19]
	v_mfma_f32_16x16x32_bf16 v[4:7], v[186:189], v[178:181], v[4:7]
	v_mfma_f32_16x16x32_bf16 v[0:3], v[198:201], v[178:181], v[0:3]
	v_mfma_f32_16x16x32_bf16 v[52:55], v[194:197], v[158:161], v[52:55]
	v_mfma_f32_16x16x32_bf16 v[48:51], v[202:205], v[158:161], v[48:51]
	v_mfma_f32_16x16x32_bf16 v[36:39], v[194:197], v[166:169], v[36:39]
	v_mfma_f32_16x16x32_bf16 v[32:35], v[202:205], v[166:169], v[32:35]
	v_mfma_f32_16x16x32_bf16 v[20:23], v[194:197], v[174:177], v[20:23]
	v_mfma_f32_16x16x32_bf16 v[16:19], v[202:205], v[174:177], v[16:19]
	v_mfma_f32_16x16x32_bf16 v[4:7], v[194:197], v[182:185], v[4:7]
	v_mfma_f32_16x16x32_bf16 v[0:3], v[202:205], v[182:185], v[0:3]
	s_setprio 0
	s_add_i32 s9, s9, 2
	s_add_u32 vcc_lo, vcc_lo, 0x100
	s_addc_u32 vcc_hi, vcc_hi, 0
	s_add_u32 s89, s89, 0x100
	s_addc_u32 s60, s60, 0
	s_cmp_gt_u32 s9, 29
	s_barrier
	s_cbranch_scc0 .LBB0_103
	v_lshl_add_u32 v134, s62, 8, v138
	v_lshl_or_b32 v136, s63, 8, v141
	v_ashrrev_i32_e32 v135, 31, v134
	v_lshlrev_b64 v[142:143], 12, v[134:135]
	v_ashrrev_i32_e32 v137, 31, v136
	v_lshl_add_u64 v[142:143], s[6:7], 0, v[142:143]
	v_lshlrev_b64 v[136:137], 1, v[136:137]
	v_lshl_add_u64 v[146:147], v[142:143], 0, v[136:137]
	global_load_dwordx4 v[148:151], v[146:147], off
	global_load_dwordx4 v[152:155], v[146:147], off offset:256
	s_mov_b64 s[100:101], 0x10000
	v_lshl_add_u64 v[210:211], v[146:147], 0, s[100:101]
	global_load_dwordx4 v[156:159], v[210:211], off
	global_load_dwordx4 v[160:163], v[210:211], off offset:256
	s_mov_b64 s[100:101], 0x20000
	v_lshl_add_u64 v[210:211], v[146:147], 0, s[100:101]
	global_load_dwordx4 v[164:167], v[210:211], off
	global_load_dwordx4 v[168:171], v[210:211], off offset:256
	s_mov_b64 s[100:101], 0x30000
	v_lshl_add_u64 v[210:211], v[146:147], 0, s[100:101]
	global_load_dwordx4 v[172:175], v[210:211], off
	global_load_dwordx4 v[176:179], v[210:211], off offset:256
	s_mov_b64 s[100:101], 0x80000
	v_lshl_add_u64 v[210:211], v[146:147], 0, s[100:101]
	global_load_dwordx4 v[180:183], v[210:211], off
	global_load_dwordx4 v[184:187], v[210:211], off offset:256
	s_mov_b64 s[100:101], 0x90000
	v_lshl_add_u64 v[210:211], v[146:147], 0, s[100:101]
	global_load_dwordx4 v[194:197], v[210:211], off
	global_load_dwordx4 v[198:201], v[210:211], off offset:256
	s_mov_b64 s[100:101], 0xa0000
	v_lshl_add_u64 v[210:211], v[146:147], 0, s[100:101]
	global_load_dwordx4 v[202:205], v[210:211], off
	global_load_dwordx4 v[206:209], v[210:211], off offset:256
	s_mov_b64 s[100:101], 0xb0000
	v_lshl_add_u64 v[210:211], v[146:147], 0, s[100:101]
	global_load_dwordx4 v[216:219], v[210:211], off
	global_load_dwordx4 v[222:225], v[210:211], off offset:256
	s_and_b64 vcc, exec, s[72:73]
	s_mov_b32 s62, s68
	s_mov_b32 s63, s70
	s_mov_b64 s[78:79], s[74:75]
	s_mov_b64 s[76:77], s[86:87]
	s_waitcnt vmcnt(0)
;   __device__ __forceinline__ bf16_t* XB() const { return (bf16_t*)(ws + 328 * MB); }
; __device__ __forceinline__ float bflo(unsigned w) { return __uint_as_float(w << 16); }
; __device__ __forceinline__ float bfhi(unsigned w) { return __uint_as_float(w & 0xffff0000u); }
; template <int MODE>
; __device__ __forceinline__ void gemm_epilogue(const Params& p, int layer, const f32x4 (&acc)[2][2][4][2], int pm, int pn, int wr, int wc, int fr, int fq) {
;     ...
;         for (int bj = 0; bj < 2; ++bj) { const int col = pn * 256 + bj * 128 + wc * 32 + 8 * fq;
;           bf16_t* xq = p.XB() + (size_t)row * DM + col; const u32x4 r = *(const u32x4*)xq; const f32x4 a0 = acc[ai][bj][m][0], a1 = acc[ai][bj][m][1];
;           const u32x4 w = {cvtpk(a0[0] + bflo(r[0]), a0[1] + bfhi(r[0])), cvtpk(a0[2] + bflo(r[1]), a0[3] + bfhi(r[1])), cvtpk(a1[0] + bflo(r[2]), a1[1] + bfhi(r[2])), cvtpk(a1[2] + bflo(r[3]), a1[3] + bfhi(r[3]))};
;           *(u32x4*)xq = w; }
	v_mov_b64_e32 v[142:143], v[148:149]
	v_mov_b64_e32 v[144:145], v[150:151]
	v_lshlrev_b32_e32 v135, 16, v142
	v_add_f32_e32 v124, v124, v135
	v_and_b32_e32 v135, 0xffff0000, v142
	v_add_f32_e32 v125, v125, v135
	v_cvt_pk_bf16_f32 v124, v124, v125
	v_lshlrev_b32_e32 v125, 16, v143
	v_add_f32_e32 v125, v126, v125
	v_and_b32_e32 v126, 0xffff0000, v143
	v_add_f32_e32 v126, v127, v126
	v_cvt_pk_bf16_f32 v125, v125, v126
	v_lshlrev_b32_e32 v126, 16, v144
	v_add_f32_e32 v120, v120, v126
	v_and_b32_e32 v126, 0xffff0000, v144
	v_add_f32_e32 v121, v121, v126
	v_cvt_pk_bf16_f32 v126, v120, v121
	v_lshlrev_b32_e32 v120, 16, v145
	v_and_b32_e32 v121, 0xffff0000, v145
	v_add_f32_e32 v120, v122, v120
	v_add_f32_e32 v121, v123, v121
	v_cvt_pk_bf16_f32 v127, v120, v121
	v_mov_b64_e32 v[120:121], v[152:153]
	v_mov_b64_e32 v[122:123], v[154:155]
	s_nop 0
	global_store_dwordx4 v[146:147], v[124:127], off
	s_nop 0
	v_lshlrev_b32_e32 v124, 16, v120
	v_and_b32_e32 v120, 0xffff0000, v120
	v_add_f32_e32 v116, v116, v124
	v_add_f32_e32 v117, v117, v120
	v_cvt_pk_bf16_f32 v116, v116, v117
	v_lshlrev_b32_e32 v117, 16, v121
	v_add_f32_e32 v117, v118, v117
	v_and_b32_e32 v118, 0xffff0000, v121
	v_add_f32_e32 v118, v119, v118
	v_cvt_pk_bf16_f32 v117, v117, v118
	v_lshlrev_b32_e32 v118, 16, v122
	v_add_f32_e32 v112, v112, v118
	v_and_b32_e32 v118, 0xffff0000, v122
	v_add_f32_e32 v113, v113, v118
	v_cvt_pk_bf16_f32 v118, v112, v113
	v_lshlrev_b32_e32 v112, 16, v123
	v_add_f32_e32 v112, v114, v112
	v_and_b32_e32 v113, 0xffff0000, v123
	v_add_f32_e32 v113, v115, v113
	v_cvt_pk_bf16_f32 v119, v112, v113
	v_or_b32_e32 v112, 16, v134
	v_ashrrev_i32_e32 v113, 31, v112
	v_lshlrev_b64 v[112:113], 12, v[112:113]
	v_lshl_add_u64 v[112:113], s[6:7], 0, v[112:113]
	global_store_dwordx4 v[146:147], v[116:119], off offset:256
	s_nop 1
	v_lshl_add_u64 v[116:117], v[112:113], 0, v[136:137]
	v_mov_b64_e32 v[112:113], v[156:157]
	v_mov_b64_e32 v[114:115], v[158:159]
	v_lshlrev_b32_e32 v118, 16, v112
	v_and_b32_e32 v112, 0xffff0000, v112
	v_add_f32_e32 v108, v108, v118
	v_add_f32_e32 v109, v109, v112
	v_cvt_pk_bf16_f32 v108, v108, v109
	v_lshlrev_b32_e32 v109, 16, v113
	v_add_f32_e32 v109, v110, v109
	v_and_b32_e32 v110, 0xffff0000, v113
	v_add_f32_e32 v110, v111, v110
	v_cvt_pk_bf16_f32 v109, v109, v110
	v_lshlrev_b32_e32 v110, 16, v114
	v_add_f32_e32 v104, v104, v110
	v_and_b32_e32 v110, 0xffff0000, v114
	v_add_f32_e32 v105, v105, v110
	v_cvt_pk_bf16_f32 v110, v104, v105
	v_lshlrev_b32_e32 v104, 16, v115
	v_and_b32_e32 v105, 0xffff0000, v115
	v_add_f32_e32 v104, v106, v104
	v_add_f32_e32 v105, v107, v105
	v_cvt_pk_bf16_f32 v111, v104, v105
	v_mov_b64_e32 v[104:105], v[160:161]
	v_mov_b64_e32 v[106:107], v[162:163]
	s_nop 0
	global_store_dwordx4 v[116:117], v[108:111], off
	s_nop 0
	v_lshlrev_b32_e32 v108, 16, v104
	v_and_b32_e32 v104, 0xffff0000, v104
	v_add_f32_e32 v100, v100, v108
	v_add_f32_e32 v101, v101, v104
	v_cvt_pk_bf16_f32 v100, v100, v101
	v_lshlrev_b32_e32 v101, 16, v105
	v_add_f32_e32 v101, v102, v101
	v_and_b32_e32 v102, 0xffff0000, v105
	v_add_f32_e32 v102, v103, v102
	v_cvt_pk_bf16_f32 v101, v101, v102
	v_lshlrev_b32_e32 v102, 16, v106
	v_add_f32_e32 v96, v96, v102
	v_and_b32_e32 v102, 0xffff0000, v106
	v_add_f32_e32 v97, v97, v102
	v_cvt_pk_bf16_f32 v102, v96, v97
	v_lshlrev_b32_e32 v96, 16, v107
	v_add_f32_e32 v96, v98, v96
	v_and_b32_e32 v97, 0xffff0000, v107
	v_add_f32_e32 v97, v99, v97
	v_cvt_pk_bf16_f32 v103, v96, v97
	v_or_b32_e32 v96, 32, v134
	v_ashrrev_i32_e32 v97, 31, v96
	v_lshlrev_b64 v[96:97], 12, v[96:97]
	v_lshl_add_u64 v[96:97], s[6:7], 0, v[96:97]
	global_store_dwordx4 v[116:117], v[100:103], off offset:256
	s_nop 1
	v_lshl_add_u64 v[100:101], v[96:97], 0, v[136:137]
	v_mov_b64_e32 v[96:97], v[164:165]
	v_mov_b64_e32 v[98:99], v[166:167]
	v_lshlrev_b32_e32 v102, 16, v96
	v_and_b32_e32 v96, 0xffff0000, v96
	v_add_f32_e32 v92, v92, v102
	v_add_f32_e32 v93, v93, v96
	v_cvt_pk_bf16_f32 v92, v92, v93
	v_lshlrev_b32_e32 v93, 16, v97
	v_add_f32_e32 v93, v94, v93
	v_and_b32_e32 v94, 0xffff0000, v97
	v_add_f32_e32 v94, v95, v94
	v_cvt_pk_bf16_f32 v93, v93, v94
	v_lshlrev_b32_e32 v94, 16, v98
	v_add_f32_e32 v88, v88, v94
	v_and_b32_e32 v94, 0xffff0000, v98
	v_add_f32_e32 v89, v89, v94
	v_cvt_pk_bf16_f32 v94, v88, v89
	v_lshlrev_b32_e32 v88, 16, v99
	v_and_b32_e32 v89, 0xffff0000, v99
	v_add_f32_e32 v88, v90, v88
	v_add_f32_e32 v89, v91, v89
	v_cvt_pk_bf16_f32 v95, v88, v89
	v_mov_b64_e32 v[88:89], v[168:169]
	v_mov_b64_e32 v[90:91], v[170:171]
	s_nop 0
	global_store_dwordx4 v[100:101], v[92:95], off
	s_nop 0
	v_lshlrev_b32_e32 v92, 16, v88
	v_and_b32_e32 v88, 0xffff0000, v88
	v_add_f32_e32 v84, v84, v92
	v_add_f32_e32 v85, v85, v88
	v_cvt_pk_bf16_f32 v84, v84, v85
	v_lshlrev_b32_e32 v85, 16, v89
	v_add_f32_e32 v85, v86, v85
	v_and_b32_e32 v86, 0xffff0000, v89
	v_add_f32_e32 v86, v87, v86
	v_cvt_pk_bf16_f32 v85, v85, v86
	v_lshlrev_b32_e32 v86, 16, v90
	v_add_f32_e32 v80, v80, v86
	v_and_b32_e32 v86, 0xffff0000, v90
	v_add_f32_e32 v81, v81, v86
	v_cvt_pk_bf16_f32 v86, v80, v81
	v_lshlrev_b32_e32 v80, 16, v91
	v_add_f32_e32 v80, v82, v80
	v_and_b32_e32 v81, 0xffff0000, v91
	v_add_f32_e32 v81, v83, v81
	v_cvt_pk_bf16_f32 v87, v80, v81
	v_or_b32_e32 v80, 48, v134
	v_ashrrev_i32_e32 v81, 31, v80
	v_lshlrev_b64 v[80:81], 12, v[80:81]
	v_lshl_add_u64 v[80:81], s[6:7], 0, v[80:81]
	global_store_dwordx4 v[100:101], v[84:87], off offset:256
	s_nop 1
	v_lshl_add_u64 v[84:85], v[80:81], 0, v[136:137]
	v_mov_b64_e32 v[80:81], v[172:173]
	v_mov_b64_e32 v[82:83], v[174:175]
	v_lshlrev_b32_e32 v86, 16, v80
	v_and_b32_e32 v80, 0xffff0000, v80
	v_add_f32_e32 v76, v76, v86
;   __device__ __forceinline__ bf16_t* XB() const { return (bf16_t*)(ws + 328 * MB); }
; __device__ __forceinline__ float bflo(unsigned w) { return __uint_as_float(w << 16); }
; __device__ __forceinline__ float bfhi(unsigned w) { return __uint_as_float(w & 0xffff0000u); }
; template <int MODE>
; __device__ __forceinline__ void gemm_epilogue(const Params& p, int layer, const f32x4 (&acc)[2][2][4][2], int pm, int pn, int wr, int wc, int fr, int fq) {
;     ...
;         for (int bj = 0; bj < 2; ++bj) { const int col = pn * 256 + bj * 128 + wc * 32 + 8 * fq;
;           bf16_t* xq = p.XB() + (size_t)row * DM + col; const u32x4 r = *(const u32x4*)xq; const f32x4 a0 = acc[ai][bj][m][0], a1 = acc[ai][bj][m][1];
;           const u32x4 w = {cvtpk(a0[0] + bflo(r[0]), a0[1] + bfhi(r[0])), cvtpk(a0[2] + bflo(r[1]), a0[3] + bfhi(r[1])), cvtpk(a1[0] + bflo(r[2]), a1[1] + bfhi(r[2])), cvtpk(a1[2] + bflo(r[3]), a1[3] + bfhi(r[3]))};
;           *(u32x4*)xq = w; }
	v_add_f32_e32 v77, v77, v80
	v_cvt_pk_bf16_f32 v76, v76, v77
	v_lshlrev_b32_e32 v77, 16, v81
	v_add_f32_e32 v77, v78, v77
	v_and_b32_e32 v78, 0xffff0000, v81
	v_add_f32_e32 v78, v79, v78
	v_cvt_pk_bf16_f32 v77, v77, v78
	v_lshlrev_b32_e32 v78, 16, v82
	v_add_f32_e32 v72, v72, v78
	v_and_b32_e32 v78, 0xffff0000, v82
	v_add_f32_e32 v73, v73, v78
	v_cvt_pk_bf16_f32 v78, v72, v73
	v_lshlrev_b32_e32 v72, 16, v83
	v_and_b32_e32 v73, 0xffff0000, v83
	v_add_f32_e32 v72, v74, v72
	v_add_f32_e32 v73, v75, v73
	v_cvt_pk_bf16_f32 v79, v72, v73
	v_mov_b64_e32 v[72:73], v[176:177]
	v_mov_b64_e32 v[74:75], v[178:179]
	s_nop 0
	global_store_dwordx4 v[84:85], v[76:79], off
	s_nop 0
	v_lshlrev_b32_e32 v76, 16, v72
	v_and_b32_e32 v72, 0xffff0000, v72
	v_add_f32_e32 v68, v68, v76
	v_add_f32_e32 v69, v69, v72
	v_cvt_pk_bf16_f32 v68, v68, v69
	v_lshlrev_b32_e32 v69, 16, v73
	v_add_f32_e32 v69, v70, v69
	v_and_b32_e32 v70, 0xffff0000, v73
	v_add_f32_e32 v70, v71, v70
	v_cvt_pk_bf16_f32 v69, v69, v70
	v_lshlrev_b32_e32 v70, 16, v74
	v_add_f32_e32 v64, v64, v70
	v_and_b32_e32 v70, 0xffff0000, v74
	v_add_f32_e32 v65, v65, v70
	v_cvt_pk_bf16_f32 v70, v64, v65
	v_lshlrev_b32_e32 v64, 16, v75
	v_add_f32_e32 v64, v66, v64
	v_and_b32_e32 v65, 0xffff0000, v75
	v_add_f32_e32 v65, v67, v65
	v_cvt_pk_bf16_f32 v71, v64, v65
	v_add_u32_e32 v64, 0x80, v134
	v_ashrrev_i32_e32 v65, 31, v64
	v_lshlrev_b64 v[64:65], 12, v[64:65]
	v_lshl_add_u64 v[64:65], s[6:7], 0, v[64:65]
	global_store_dwordx4 v[84:85], v[68:71], off offset:256
	s_nop 1
	v_lshl_add_u64 v[68:69], v[64:65], 0, v[136:137]
	v_mov_b64_e32 v[64:65], v[180:181]
	v_mov_b64_e32 v[66:67], v[182:183]
	v_lshlrev_b32_e32 v70, 16, v64
	v_and_b32_e32 v64, 0xffff0000, v64
	v_add_f32_e32 v60, v60, v70
	v_add_f32_e32 v61, v61, v64
	v_cvt_pk_bf16_f32 v60, v60, v61
	v_lshlrev_b32_e32 v61, 16, v65
	v_add_f32_e32 v61, v62, v61
	v_and_b32_e32 v62, 0xffff0000, v65
	v_add_f32_e32 v62, v63, v62
	v_cvt_pk_bf16_f32 v61, v61, v62
	v_lshlrev_b32_e32 v62, 16, v66
	v_add_f32_e32 v56, v56, v62
	v_and_b32_e32 v62, 0xffff0000, v66
	v_add_f32_e32 v57, v57, v62
	v_cvt_pk_bf16_f32 v62, v56, v57
	v_lshlrev_b32_e32 v56, 16, v67
	v_and_b32_e32 v57, 0xffff0000, v67
	v_add_f32_e32 v56, v58, v56
	v_add_f32_e32 v57, v59, v57
	v_cvt_pk_bf16_f32 v63, v56, v57
	v_mov_b64_e32 v[56:57], v[184:185]
	v_mov_b64_e32 v[58:59], v[186:187]
	s_nop 0
	global_store_dwordx4 v[68:69], v[60:63], off
	s_nop 0
	v_lshlrev_b32_e32 v60, 16, v56
	v_and_b32_e32 v56, 0xffff0000, v56
	v_add_f32_e32 v52, v52, v60
	v_add_f32_e32 v53, v53, v56
	v_cvt_pk_bf16_f32 v52, v52, v53
	v_lshlrev_b32_e32 v53, 16, v57
	v_add_f32_e32 v53, v54, v53
	v_and_b32_e32 v54, 0xffff0000, v57
	v_add_f32_e32 v54, v55, v54
	v_cvt_pk_bf16_f32 v53, v53, v54
	v_lshlrev_b32_e32 v54, 16, v58
	v_add_f32_e32 v48, v48, v54
	v_and_b32_e32 v54, 0xffff0000, v58
	v_add_f32_e32 v49, v49, v54
	v_cvt_pk_bf16_f32 v54, v48, v49
	v_lshlrev_b32_e32 v48, 16, v59
	v_add_f32_e32 v48, v50, v48
	v_and_b32_e32 v49, 0xffff0000, v59
	v_add_f32_e32 v49, v51, v49
	v_cvt_pk_bf16_f32 v55, v48, v49
	v_add_u32_e32 v48, 0x90, v134
	v_ashrrev_i32_e32 v49, 31, v48
	v_lshlrev_b64 v[48:49], 12, v[48:49]
	v_lshl_add_u64 v[48:49], s[6:7], 0, v[48:49]
	global_store_dwordx4 v[68:69], v[52:55], off offset:256
	s_nop 1
	v_lshl_add_u64 v[52:53], v[48:49], 0, v[136:137]
	v_mov_b64_e32 v[48:49], v[194:195]
	v_mov_b64_e32 v[50:51], v[196:197]
	v_lshlrev_b32_e32 v54, 16, v48
	v_and_b32_e32 v48, 0xffff0000, v48
	v_add_f32_e32 v44, v44, v54
	v_add_f32_e32 v45, v45, v48
	v_cvt_pk_bf16_f32 v44, v44, v45
	v_lshlrev_b32_e32 v45, 16, v49
	v_add_f32_e32 v45, v46, v45
	v_and_b32_e32 v46, 0xffff0000, v49
	v_add_f32_e32 v46, v47, v46
	v_cvt_pk_bf16_f32 v45, v45, v46
	v_lshlrev_b32_e32 v46, 16, v50
	v_add_f32_e32 v40, v40, v46
	v_and_b32_e32 v46, 0xffff0000, v50
	v_add_f32_e32 v41, v41, v46
	v_cvt_pk_bf16_f32 v46, v40, v41
	v_lshlrev_b32_e32 v40, 16, v51
	v_and_b32_e32 v41, 0xffff0000, v51
	v_add_f32_e32 v40, v42, v40
	v_add_f32_e32 v41, v43, v41
	v_cvt_pk_bf16_f32 v47, v40, v41
	v_mov_b64_e32 v[40:41], v[198:199]
	v_mov_b64_e32 v[42:43], v[200:201]
	s_nop 0
	global_store_dwordx4 v[52:53], v[44:47], off
	s_nop 0
	v_lshlrev_b32_e32 v44, 16, v40
	v_and_b32_e32 v40, 0xffff0000, v40
	v_add_f32_e32 v36, v36, v44
;   __device__ __forceinline__ bf16_t* XB() const { return (bf16_t*)(ws + 328 * MB); }
; __device__ __forceinline__ float bflo(unsigned w) { return __uint_as_float(w << 16); }
; __device__ __forceinline__ float bfhi(unsigned w) { return __uint_as_float(w & 0xffff0000u); }
; #define G_WAIT_V(n) asm volatile("s_waitcnt vmcnt(" #n ")" ::: "memory")
; #define G_BAR __builtin_amdgcn_s_barrier()
; template <int MODE>
; __device__ __forceinline__ void gemm_epilogue(const Params& p, int layer, const f32x4 (&acc)[2][2][4][2], int pm, int pn, int wr, int wc, int fr, int fq) {
;     ...
;         for (int bj = 0; bj < 2; ++bj) { const int col = pn * 256 + bj * 128 + wc * 32 + 8 * fq;
;           bf16_t* xq = p.XB() + (size_t)row * DM + col; const u32x4 r = *(const u32x4*)xq; const f32x4 a0 = acc[ai][bj][m][0], a1 = acc[ai][bj][m][1];
;           const u32x4 w = {cvtpk(a0[0] + bflo(r[0]), a0[1] + bfhi(r[0])), cvtpk(a0[2] + bflo(r[1]), a0[3] + bfhi(r[1])), cvtpk(a1[0] + bflo(r[2]), a1[1] + bfhi(r[2])), cvtpk(a1[2] + bflo(r[3]), a1[3] + bfhi(r[3]))};
;           *(u32x4*)xq = w; }
; template <int MODE>
; __device__ __forceinline__ void gemm_phase(const Params& p, int layer, char* lds_generic) {
;     ...
;     if (!has_next) break;
; #pragma unroll
;     for (int a = 0; a < 2; ++a)
; #pragma unroll
;       for (int b = 0; b < 2; ++b)
; #pragma unroll
;         for (int m = 0; m < 4; ++m)
; #pragma unroll
;           for (int n = 0; n < 2; ++n) acc[a][b][m][n] = (f32x4){0.f, 0.f, 0.f, 0.f};
;     cpm = npm; cpn = npn; cA = nA; cB = nB; ++ui;
;   }
;   G_WAIT_V(0);
;   if (wr == 0) G_BAR;
;   G_BAR;
	v_add_f32_e32 v37, v37, v40
	v_cvt_pk_bf16_f32 v36, v36, v37
	v_lshlrev_b32_e32 v37, 16, v41
	v_add_f32_e32 v37, v38, v37
	v_and_b32_e32 v38, 0xffff0000, v41
	v_add_f32_e32 v38, v39, v38
	v_cvt_pk_bf16_f32 v37, v37, v38
	v_lshlrev_b32_e32 v38, 16, v42
	v_add_f32_e32 v32, v32, v38
	v_and_b32_e32 v38, 0xffff0000, v42
	v_add_f32_e32 v33, v33, v38
	v_cvt_pk_bf16_f32 v38, v32, v33
	v_lshlrev_b32_e32 v32, 16, v43
	v_add_f32_e32 v32, v34, v32
	v_and_b32_e32 v33, 0xffff0000, v43
	v_add_f32_e32 v33, v35, v33
	v_cvt_pk_bf16_f32 v39, v32, v33
	v_add_u32_e32 v32, 0xa0, v134
	v_ashrrev_i32_e32 v33, 31, v32
	v_lshlrev_b64 v[32:33], 12, v[32:33]
	v_lshl_add_u64 v[32:33], s[6:7], 0, v[32:33]
	global_store_dwordx4 v[52:53], v[36:39], off offset:256
	s_nop 1
	v_lshl_add_u64 v[36:37], v[32:33], 0, v[136:137]
	v_mov_b64_e32 v[32:33], v[202:203]
	v_mov_b64_e32 v[34:35], v[204:205]
	v_lshlrev_b32_e32 v38, 16, v32
	v_and_b32_e32 v32, 0xffff0000, v32
	v_add_f32_e32 v28, v28, v38
	v_add_f32_e32 v29, v29, v32
	v_cvt_pk_bf16_f32 v28, v28, v29
	v_lshlrev_b32_e32 v29, 16, v33
	v_add_f32_e32 v29, v30, v29
	v_and_b32_e32 v30, 0xffff0000, v33
	v_add_f32_e32 v30, v31, v30
	v_cvt_pk_bf16_f32 v29, v29, v30
	v_lshlrev_b32_e32 v30, 16, v34
	v_add_f32_e32 v24, v24, v30
	v_and_b32_e32 v30, 0xffff0000, v34
	v_add_f32_e32 v25, v25, v30
	v_cvt_pk_bf16_f32 v30, v24, v25
	v_lshlrev_b32_e32 v24, 16, v35
	v_and_b32_e32 v25, 0xffff0000, v35
	v_add_f32_e32 v24, v26, v24
	v_add_f32_e32 v25, v27, v25
	v_cvt_pk_bf16_f32 v31, v24, v25
	v_mov_b64_e32 v[24:25], v[206:207]
	v_mov_b64_e32 v[26:27], v[208:209]
	s_nop 0
	global_store_dwordx4 v[36:37], v[28:31], off
	s_nop 0
	v_lshlrev_b32_e32 v28, 16, v24
	v_and_b32_e32 v24, 0xffff0000, v24
	v_add_f32_e32 v20, v20, v28
	v_add_f32_e32 v21, v21, v24
	v_cvt_pk_bf16_f32 v20, v20, v21
	v_lshlrev_b32_e32 v21, 16, v25
	v_add_f32_e32 v21, v22, v21
	v_and_b32_e32 v22, 0xffff0000, v25
	v_add_f32_e32 v22, v23, v22
	v_cvt_pk_bf16_f32 v21, v21, v22
	v_lshlrev_b32_e32 v22, 16, v26
	v_add_f32_e32 v16, v16, v22
	v_and_b32_e32 v22, 0xffff0000, v26
	v_add_f32_e32 v17, v17, v22
	v_cvt_pk_bf16_f32 v22, v16, v17
	v_lshlrev_b32_e32 v16, 16, v27
	v_add_f32_e32 v16, v18, v16
	v_and_b32_e32 v17, 0xffff0000, v27
	v_add_f32_e32 v17, v19, v17
	v_cvt_pk_bf16_f32 v23, v16, v17
	v_add_u32_e32 v16, 0xb0, v134
	v_ashrrev_i32_e32 v17, 31, v16
	v_lshlrev_b64 v[16:17], 12, v[16:17]
	v_lshl_add_u64 v[16:17], s[6:7], 0, v[16:17]
	global_store_dwordx4 v[36:37], v[20:23], off offset:256
	s_nop 1
	v_lshl_add_u64 v[20:21], v[16:17], 0, v[136:137]
	v_mov_b64_e32 v[16:17], v[216:217]
	v_mov_b64_e32 v[18:19], v[218:219]
	v_lshlrev_b32_e32 v22, 16, v16
	v_and_b32_e32 v16, 0xffff0000, v16
	v_add_f32_e32 v12, v12, v22
	v_add_f32_e32 v13, v13, v16
	v_cvt_pk_bf16_f32 v12, v12, v13
	v_lshlrev_b32_e32 v13, 16, v17
	v_add_f32_e32 v13, v14, v13
	v_and_b32_e32 v14, 0xffff0000, v17
	v_add_f32_e32 v14, v15, v14
	v_cvt_pk_bf16_f32 v13, v13, v14
	v_lshlrev_b32_e32 v14, 16, v18
	v_add_f32_e32 v8, v8, v14
	v_and_b32_e32 v14, 0xffff0000, v18
	v_add_f32_e32 v9, v9, v14
	v_cvt_pk_bf16_f32 v14, v8, v9
	v_lshlrev_b32_e32 v8, 16, v19
	v_and_b32_e32 v9, 0xffff0000, v19
	v_add_f32_e32 v8, v10, v8
	v_add_f32_e32 v9, v11, v9
	v_cvt_pk_bf16_f32 v15, v8, v9
	v_mov_b64_e32 v[8:9], v[222:223]
	v_mov_b64_e32 v[10:11], v[224:225]
	s_nop 0
	global_store_dwordx4 v[20:21], v[12:15], off
	s_nop 0
	v_lshlrev_b32_e32 v12, 16, v8
	v_and_b32_e32 v8, 0xffff0000, v8
	v_add_f32_e32 v4, v4, v12
	v_add_f32_e32 v5, v5, v8
	v_cvt_pk_bf16_f32 v4, v4, v5
	v_lshlrev_b32_e32 v5, 16, v9
	v_add_f32_e32 v5, v6, v5
	v_and_b32_e32 v6, 0xffff0000, v9
	v_add_f32_e32 v6, v7, v6
	v_cvt_pk_bf16_f32 v5, v5, v6
	v_lshlrev_b32_e32 v6, 16, v10
	v_add_f32_e32 v0, v0, v6
	v_and_b32_e32 v6, 0xffff0000, v10
	v_add_f32_e32 v1, v1, v6
	v_cvt_pk_bf16_f32 v6, v0, v1
	v_lshlrev_b32_e32 v0, 16, v11
	v_and_b32_e32 v1, 0xffff0000, v11
	v_add_f32_e32 v0, v2, v0
	v_add_f32_e32 v1, v3, v1
	v_cvt_pk_bf16_f32 v7, v0, v1
	global_store_dwordx4 v[20:21], v[4:7], off offset:256
	s_cbranch_vccz .LBB0_100
	s_waitcnt vmcnt(0)
	v_readlane_b32 s82, v254, 24
	s_cmpk_gt_u32 s15, 0xff
	v_readlane_b32 s83, v254, 25
	s_mov_b64 s[84:85], s[16:17]
	v_readlane_b32 s63, v254, 27
	s_cbranch_scc1 .LBB0_107
	s_barrier

; __global__ void __launch_bounds__(512) fwd_mega(Params pin, int first, int last) {
;   __shared__ __attribute__((aligned(16))) char lds[LDS_BYTES];
	.amdhsa_kernel _Z8fwd_mega6Paramsii
		.amdhsa_group_segment_fixed_size 139264
		.amdhsa_private_segment_fixed_size 0
		.amdhsa_kernarg_size 456
		.amdhsa_user_sgpr_count 2
		.amdhsa_user_sgpr_dispatch_ptr 0
		.amdhsa_user_sgpr_queue_ptr 0
		.amdhsa_user_sgpr_kernarg_segment_ptr 1
		.amdhsa_user_sgpr_dispatch_id 0
		.amdhsa_user_sgpr_kernarg_preload_length 0
		.amdhsa_user_sgpr_kernarg_preload_offset 0
		.amdhsa_user_sgpr_private_segment_size 0
		.amdhsa_uses_dynamic_stack 0
		.amdhsa_enable_private_segment 0
		.amdhsa_system_sgpr_workgroup_id_x 1
		.amdhsa_system_sgpr_workgroup_id_y 0
		.amdhsa_system_sgpr_workgroup_id_z 0
		.amdhsa_system_sgpr_workgroup_info 0
		.amdhsa_system_vgpr_workitem_id 2
		.amdhsa_next_free_vgpr 256
		.amdhsa_next_free_sgpr 102
		.amdhsa_accum_offset 256
		.amdhsa_reserve_vcc 1
		.amdhsa_float_round_mode_32 0
		.amdhsa_float_round_mode_16_64 0
		.amdhsa_float_denorm_mode_32 3
		.amdhsa_float_denorm_mode_16_64 3
		.amdhsa_dx10_clamp 1
		.amdhsa_ieee_mode 1
		.amdhsa_fp16_overflow 0
		.amdhsa_tg_split 0
		.amdhsa_exception_fp_ieee_invalid_op 0
		.amdhsa_exception_fp_denorm_src 0
		.amdhsa_exception_fp_ieee_div_zero 0
		.amdhsa_exception_fp_ieee_overflow 0
		.amdhsa_exception_fp_ieee_underflow 0
		.amdhsa_exception_fp_ieee_inexact 0
		.amdhsa_exception_int_div_zero 0
	.end_amdhsa_kernel

; __global__ void __launch_bounds__(512) fwd_mega(Params pin, int first, int last) {
;   __shared__ __attribute__((aligned(16))) char lds[LDS_BYTES];
amdhsa.kernels:
  - .agpr_count:     0
    .args:
      - .offset:         0
        .size:           192
        .value_kind:     by_value
      - .offset:         192
        .size:           4
        .value_kind:     by_value
      - .offset:         196
        .size:           4
        .value_kind:     by_value
      - .offset:         200
        .size:           4
        .value_kind:     hidden_block_count_x
      - .offset:         204
        .size:           4
        .value_kind:     hidden_block_count_y
      - .offset:         208
        .size:           4
        .value_kind:     hidden_block_count_z
      - .offset:         212
        .size:           2
        .value_kind:     hidden_group_size_x
      - .offset:         214
        .size:           2
        .value_kind:     hidden_group_size_y
      - .offset:         216
        .size:           2
        .value_kind:     hidden_group_size_z
      - .offset:         218
        .size:           2
        .value_kind:     hidden_remainder_x
      - .offset:         220
        .size:           2
        .value_kind:     hidden_remainder_y
      - .offset:         222
        .size:           2
        .value_kind:     hidden_remainder_z
      - .offset:         240
        .size:           8
        .value_kind:     hidden_global_offset_x
      - .offset:         248
        .size:           8
        .value_kind:     hidden_global_offset_y
      - .offset:         256
        .size:           8
        .value_kind:     hidden_global_offset_z
      - .offset:         264
        .size:           2
        .value_kind:     hidden_grid_dims
      - .offset:         288
        .size:           8
        .value_kind:     hidden_multigrid_sync_arg
    .group_segment_fixed_size: 139264
    .kernarg_segment_align: 8
    .kernarg_segment_size: 456
    .language:       OpenCL C
    .language_version:
      - 2
      - 0
    .max_flat_workgroup_size: 512
    .name:           _Z8fwd_mega6Paramsii
    .private_segment_fixed_size: 0
    .sgpr_count:     108
    .sgpr_spill_count: 79
    .symbol:         _Z8fwd_mega6Paramsii.kd
    .uniform_work_group_size: 1
    .uses_dynamic_stack: false
    .vgpr_count:     256
    .vgpr_spill_count: 0
    .wavefront_size: 64
